# P5 balance: 4th prompt row of the sample-row waves handed to waves 2,3
# baseline (speedup 1.0000x reference)
; __device__ __forceinline__ void p5_final_norm(Frame& F, float* dst, const f32x4 (&xpre)[16]) {
;     const int gw = F.vcu * NWAVES + F.wave, NGW = F.G * NWAVES;
;     for (int r = F.wave * F.G + F.vcu; r < MS; r += NGW) p5_row<true>(F, MP + r, dst);
.LBB0_833:
	s_mov_b32 s100, 1
	s_ashr_i32 s33, s4, 6
	s_load_dwordx2 s[10:11], s[0:1], 0xb0
	s_load_dwordx2 s[8:9], s[0:1], 0x0
	s_load_dwordx4 s[4:7], s[0:1], 0xa0
	s_mul_i32 s12, s33, s3
	v_and_b32_e32 v0, 63, v0
	s_add_i32 s12, s2, s12
	s_cmpk_gt_i32 s12, 0x1ff
	v_lshlrev_b32_e32 v130, 5, v0
	v_lshlrev_b32_e32 v0, 4, v0
	s_cbranch_scc1 .LBB0_838
	s_load_dwordx2 s[0:1], s[0:1], 0x10
	v_mov_b32_e32 v131, 0
	s_ashr_i32 s13, s12, 31
	s_waitcnt lgkmcnt(0)
	v_lshl_add_u64 v[132:133], s[4:5], 0, v[130:131]
	s_mov_b64 s[14:15], 0x1000
	v_lshl_add_u64 v[146:147], s[0:1], 0, v[130:131]
	s_lshl_b64 s[0:1], s[12:13], 13
	s_add_u32 s0, s10, s0
	s_mov_b64 s[16:17], 0x1800
	s_mov_b64 s[18:19], 0x2000
	s_mov_b64 s[20:21], 0x2800
	s_mov_b64 s[22:23], 0x3000
	s_mov_b64 s[24:25], 0x3800
	v_mov_b32_e32 v1, v131
	s_addc_u32 s1, s11, s1
	s_ashr_i32 s29, s28, 31
	v_lshl_add_u64 v[134:135], v[132:133], 0, s[14:15]
	v_lshl_add_u64 v[136:137], v[132:133], 0, s[16:17]
	v_lshl_add_u64 v[138:139], v[132:133], 0, s[18:19]
	v_lshl_add_u64 v[140:141], v[132:133], 0, s[20:21]
	v_lshl_add_u64 v[142:143], v[132:133], 0, s[22:23]
	v_lshl_add_u64 v[144:145], v[132:133], 0, s[24:25]
	v_lshl_add_u64 v[148:149], s[6:7], 0, v[130:131]
	v_lshl_add_u64 v[150:151], s[0:1], 0, v[0:1]
	s_lshl_b64 s[26:27], s[28:29], 13
	s_movk_i32 s29, 0x1000
	s_movk_i32 s34, 0x2000
	s_movk_i32 s35, 0x3000
	s_mov_b32 s36, 0x13000000
	s_mov_b32 s37, 0x13001000
	s_mov_b32 s38, 0x13400000
	s_mov_b32 s39, 0x13401000
	v_mov_b32_e32 v1, 0x358637bd
	s_mov_b32 s40, 0xf800000
	v_mov_b32_e32 v131, 0x260
	s_mov_b64 s[30:31], 0x8000000
	s_mov_b32 s41, 0x8001000
	s_mov_b32 s42, 0x8002000
	s_mov_b32 s43, 0x8003000
	v_mov_b32_e32 v152, 0x39800000

; #define GAS __attribute__((address_space(1)))
; __device__ __forceinline__ float h_lo(unsigned w) { return (float)__builtin_bit_cast(_Float16, (unsigned short)(w & 0xffffu)); }
; __device__ __forceinline__ float h_hi(unsigned w) { return (float)__builtin_bit_cast(_Float16, (unsigned short)(w >> 16)); }
; template <bool SAMPLE, bool PRE = false> __device__ __forceinline__ void p5_row(Frame& F, int m, float* dst, const f32x4* xpre = nullptr) {
;     f32x4 v[16];
;     const GAS f32x4* x8 = (const GAS f32x4*)((SAMPLE ? F.in[2] + (size_t)(m - MP) * DM : F.in[0] + (size_t)m * DM)) + 2 * F.lane;
;     if (!SAMPLE) {
;         const GAS u32x4* yr = (const GAS u32x4*)(F.ws + WS_YH + (size_t)m * DM * 2) + F.lane;
;         u32x4 w[8];
; #pragma unroll
;         for (int j = 0; j < 8; ++j) { w[j] = yr[64 * j]; if constexpr (PRE) { v[2 * j] = xpre[2 * j]; v[2 * j + 1] = xpre[2 * j + 1]; } else { v[2 * j] = x8[128 * j]; v[2 * j + 1] = x8[128 * j + 1]; } }
; #pragma unroll
;         for (int j = 0; j < 8; ++j) { v[2 * j] += (f32x4){h_lo(w[j].x), h_hi(w[j].x), h_lo(w[j].y), h_hi(w[j].y)}; v[2 * j + 1] += (f32x4){h_lo(w[j].z), h_hi(w[j].z), h_lo(w[j].w), h_hi(w[j].w)}; }
; __device__ __forceinline__ void p5_final_norm(Frame& F, float* dst, const f32x4 (&xpre)[16]) {
;     ...
;     if (gw < MP) p5_row<false, true>(F, gw, dst, xpre);
;     for (int m = gw + NGW; m < MP; m += NGW) p5_row<false>(F, m, dst);
.LBB0_840:
	s_add_i32 s0, s12, s28
	s_cmpk_gt_i32 s0, 0x1fff
	s_cbranch_scc1 .LBB0_843
	s_mov_b32 s100, 0
	s_movk_i32 s99, 0x2000
	s_cmp_lt_u32 s33, 2
	s_cselect_b32 s99, 0x1800, s99
	s_add_i32 s3, s3, s2
	s_lshl_b32 s1, s3, 3
	s_add_i32 s22, s33, s1
	s_ashr_i32 s1, s0, 31
	s_lshl_b64 s[2:3], s[0:1], 13
	v_mov_b32_e32 v131, 0
	s_waitcnt lgkmcnt(0)
	s_add_u32 s2, s10, s2
	v_mov_b32_e32 v1, v131
	s_addc_u32 s3, s11, s3
	v_lshl_add_u64 v[0:1], s[2:3], 0, v[0:1]
	s_mov_b64 s[2:3], 0x17200000
	s_ashr_i32 s29, s28, 31
	v_lshl_add_u64 v[94:95], v[0:1], 0, s[2:3]
	s_lshl_b64 s[2:3], s[28:29], 13
	s_lshl_b64 s[0:1], s[0:1], 14
	s_add_u32 s6, s6, s0
	s_addc_u32 s7, s7, s1
	s_lshl_b64 s[10:11], s[28:29], 14
	v_lshl_add_u64 v[80:81], s[4:5], 0, v[130:131]
	s_mov_b64 s[4:5], 0x1000
	s_mov_b64 s[12:13], 0x1800
	s_mov_b64 s[14:15], 0x2000
	s_mov_b64 s[16:17], 0x2800
	s_mov_b64 s[18:19], 0x3000
	s_mov_b64 s[20:21], 0x3800
	s_add_u32 s8, s8, s0
	v_lshl_add_u64 v[82:83], v[80:81], 0, s[4:5]
	v_lshl_add_u64 v[84:85], v[80:81], 0, s[12:13]
	v_lshl_add_u64 v[86:87], v[80:81], 0, s[14:15]
	v_lshl_add_u64 v[88:89], v[80:81], 0, s[16:17]
	v_lshl_add_u64 v[90:91], v[80:81], 0, s[18:19]
	v_lshl_add_u64 v[92:93], v[80:81], 0, s[20:21]
	s_addc_u32 s9, s9, s1
	s_movk_i32 s23, 0x1000
	s_movk_i32 s24, 0x2000
	s_movk_i32 s25, 0x3000
	v_mov_b32_e32 v106, 0x358637bd
	v_mov_b32_e32 v107, 0x39800000
	s_mov_b32 s26, 0xf800000
	v_mov_b32_e32 v108, 0x260
.LBB0_842:
	v_lshl_add_u64 v[96:97], s[8:9], 0, v[130:131]
	global_load_dwordx4 v[12:15], v[94:95], off
	global_load_dwordx4 v[8:11], v[94:95], off offset:1024
	global_load_dwordx4 v[0:3], v[94:95], off offset:2048
	global_load_dwordx4 v[4:7], v[94:95], off offset:3072
	v_add_co_u32_e32 v136, vcc, 0x1000, v96
	v_lshl_add_u64 v[132:133], v[96:97], 0, s[4:5]
	s_nop 0
	v_addc_co_u32_e32 v137, vcc, 0, v97, vcc
	v_add_co_u32_e32 v156, vcc, 0x1000, v94
	v_lshl_add_u64 v[140:141], v[96:97], 0, s[12:13]
	s_nop 0
	v_addc_co_u32_e32 v157, vcc, 0, v95, vcc
	global_load_dwordx4 v[68:71], v[80:81], off offset:16
	global_load_dwordx4 v[76:79], v[80:81], off
	global_load_dwordx4 v[60:63], v[80:81], off offset:2064
	global_load_dwordx4 v[72:75], v[80:81], off offset:2048
	global_load_dwordx4 v[52:55], v[82:83], off offset:16
	global_load_dwordx4 v[64:67], v[82:83], off
	global_load_dwordx4 v[44:47], v[84:85], off offset:16
	global_load_dwordx4 v[56:59], v[84:85], off
	global_load_dwordx4 v[36:39], v[86:87], off offset:16
	global_load_dwordx4 v[48:51], v[86:87], off
	global_load_dwordx4 v[28:31], v[88:89], off offset:16
	global_load_dwordx4 v[40:43], v[88:89], off
	global_load_dwordx4 v[20:23], v[90:91], off offset:16
	global_load_dwordx4 v[32:35], v[90:91], off
	global_load_dwordx4 v[16:19], v[92:93], off offset:16
	global_load_dwordx4 v[24:27], v[92:93], off
	global_load_dwordx4 v[110:113], v[96:97], off offset:16
	global_load_dwordx4 v[114:117], v[96:97], off
	global_load_dwordx4 v[118:121], v[96:97], off offset:2064
	global_load_dwordx4 v[122:125], v[96:97], off offset:2048
	global_load_dwordx4 v[126:129], v[136:137], off
	s_nop 0
	global_load_dwordx4 v[132:135], v[132:133], off offset:16
	s_nop 0
	global_load_dwordx4 v[136:139], v[136:137], off offset:2048
	s_nop 0
	global_load_dwordx4 v[140:143], v[140:141], off offset:16
	s_nop 0
	global_load_dwordx4 v[144:147], v[156:157], off
	global_load_dwordx4 v[148:151], v[156:157], off offset:1024
	global_load_dwordx4 v[152:155], v[156:157], off offset:2048
	v_add_co_u32_e32 v168, vcc, 0x2000, v96
	global_load_dwordx4 v[156:159], v[156:157], off offset:3072
	v_lshl_add_u64 v[164:165], v[96:97], 0, s[14:15]
	v_lshl_add_u64 v[172:173], v[96:97], 0, s[16:17]
	v_addc_co_u32_e32 v169, vcc, 0, v97, vcc
	global_load_dwordx4 v[160:163], v[168:169], off
	s_nop 0
	global_load_dwordx4 v[164:167], v[164:165], off offset:16
	s_nop 0
	global_load_dwordx4 v[168:171], v[168:169], off offset:2048
	s_nop 0
	global_load_dwordx4 v[172:175], v[172:173], off offset:16
	v_lshl_add_u64 v[180:181], v[96:97], 0, s[18:19]
	v_lshl_add_u64 v[188:189], v[96:97], 0, s[20:21]
	v_add_co_u32_e32 v96, vcc, 0x3000, v96
	v_lshl_add_u64 v[98:99], s[6:7], 0, v[130:131]
	s_nop 0
	v_addc_co_u32_e32 v97, vcc, 0, v97, vcc
	global_load_dwordx4 v[176:179], v[96:97], off
	s_nop 0
	global_load_dwordx4 v[180:183], v[180:181], off offset:16
	s_nop 0
	global_load_dwordx4 v[184:187], v[96:97], off offset:2048
	s_nop 0
	global_load_dwordx4 v[188:191], v[188:189], off offset:16
	v_add_co_u32_e64 v104, s[0:1], s23, v98
	v_mov_b32_e32 v109, 0
	s_nop 0
	v_addc_co_u32_e64 v105, s[0:1], 0, v99, s[0:1]
	v_add_co_u32_e64 v102, s[0:1], s24, v98
	v_mov_b32_e32 v208, 0
	s_nop 0
	v_addc_co_u32_e64 v103, s[0:1], 0, v99, s[0:1]
	v_add_co_u32_e64 v100, s[0:1], s25, v98
	s_add_i32 s22, s22, s28
	s_nop 0
	v_addc_co_u32_e64 v101, s[0:1], 0, v99, s[0:1]
	s_add_u32 s6, s6, s10
	s_addc_u32 s7, s7, s11
	s_add_u32 s8, s8, s10
	s_addc_u32 s9, s9, s11
	v_lshl_add_u64 v[94:95], v[94:95], 0, s[2:3]
	s_cmp_lt_i32 s22, s99
	s_waitcnt vmcnt(39)
	v_cvt_f32_f16_sdwa v97, v12 dst_sel:DWORD dst_unused:UNUSED_PAD src0_sel:WORD_1
	v_cvt_f32_f16_e32 v96, v12
	v_cvt_f32_f16_sdwa v193, v13 dst_sel:DWORD dst_unused:UNUSED_PAD src0_sel:WORD_1
	v_cvt_f32_f16_e32 v192, v13
	v_cvt_f32_f16_sdwa v13, v14 dst_sel:DWORD dst_unused:UNUSED_PAD src0_sel:WORD_1
	v_cvt_f32_f16_e32 v12, v14
	v_cvt_f32_f16_sdwa v195, v15 dst_sel:DWORD dst_unused:UNUSED_PAD src0_sel:WORD_1
	v_cvt_f32_f16_e32 v194, v15
	s_waitcnt vmcnt(38)
; #define GAS __attribute__((address_space(1)))
; __device__ __forceinline__ float h_lo(unsigned w) { return (float)__builtin_bit_cast(_Float16, (unsigned short)(w & 0xffffu)); }
; __device__ __forceinline__ float h_hi(unsigned w) { return (float)__builtin_bit_cast(_Float16, (unsigned short)(w >> 16)); }
; template <bool SAMPLE, bool PRE = false> __device__ __forceinline__ void p5_row(Frame& F, int m, float* dst, const f32x4* xpre = nullptr) {
;     ...
;         for (int j = 0; j < 8; ++j) { w[j] = yr[64 * j]; if constexpr (PRE) { v[2 * j] = xpre[2 * j]; v[2 * j + 1] = xpre[2 * j + 1]; } else { v[2 * j] = x8[128 * j]; v[2 * j + 1] = x8[128 * j + 1]; } }
; #pragma unroll
;         for (int j = 0; j < 8; ++j) { v[2 * j] += (f32x4){h_lo(w[j].x), h_hi(w[j].x), h_lo(w[j].y), h_hi(w[j].y)}; v[2 * j + 1] += (f32x4){h_lo(w[j].z), h_hi(w[j].z), h_lo(w[j].w), h_hi(w[j].w)}; }
;     } else {
; #pragma unroll
;         for (int j = 0; j < 8; ++j) { v[2 * j] = x8[128 * j]; v[2 * j + 1] = x8[128 * j + 1]; }
; #pragma unroll 2
;         for (int p = 0; p < 8; ++p) { const GAS u32x4* pr = (const GAS u32x4*)(F.ws + WS_SLAB + ((size_t)p * MS + (m - MP)) * DM * 2) + F.lane;
;             u32x4 w[8];
; #pragma unroll
;             for (int j = 0; j < 8; ++j) w[j] = pr[64 * j];
; #pragma unroll
;             for (int j = 0; j < 8; ++j) { v[2 * j] += (f32x4){h_lo(w[j].x), h_hi(w[j].x), h_lo(w[j].y), h_hi(w[j].y)}; v[2 * j + 1] += (f32x4){h_lo(w[j].z), h_hi(w[j].z), h_lo(w[j].w), h_hi(w[j].w)}; } }
;     }
;     float s = 0.f;
; #pragma unroll
;     for (int j = 0; j < 16; ++j) s += (v[j].x * v[j].x + v[j].y * v[j].y) + (v[j].z * v[j].z + v[j].w * v[j].w);
;     const float rstd = 1.0f / sqrtf(wave_sum(s) * (1.0f / DM) + EPS);
	v_cvt_f32_f16_sdwa v15, v8 dst_sel:DWORD dst_unused:UNUSED_PAD src0_sel:WORD_1
	v_cvt_f32_f16_e32 v14, v8
	v_cvt_f32_f16_sdwa v197, v9 dst_sel:DWORD dst_unused:UNUSED_PAD src0_sel:WORD_1
	v_cvt_f32_f16_e32 v196, v9
	v_cvt_f32_f16_sdwa v9, v10 dst_sel:DWORD dst_unused:UNUSED_PAD src0_sel:WORD_1
	v_cvt_f32_f16_e32 v8, v10
	v_cvt_f32_f16_sdwa v199, v11 dst_sel:DWORD dst_unused:UNUSED_PAD src0_sel:WORD_1
	v_cvt_f32_f16_e32 v198, v11
	s_waitcnt vmcnt(37)
	v_cvt_f32_f16_sdwa v11, v0 dst_sel:DWORD dst_unused:UNUSED_PAD src0_sel:WORD_1
	v_cvt_f32_f16_e32 v10, v0
	v_cvt_f32_f16_sdwa v201, v1 dst_sel:DWORD dst_unused:UNUSED_PAD src0_sel:WORD_1
	v_cvt_f32_f16_e32 v200, v1
	v_cvt_f32_f16_sdwa v1, v2 dst_sel:DWORD dst_unused:UNUSED_PAD src0_sel:WORD_1
	v_cvt_f32_f16_e32 v0, v2
	v_cvt_f32_f16_sdwa v203, v3 dst_sel:DWORD dst_unused:UNUSED_PAD src0_sel:WORD_1
	v_cvt_f32_f16_e32 v202, v3
	s_waitcnt vmcnt(36)
	v_cvt_f32_f16_sdwa v3, v4 dst_sel:DWORD dst_unused:UNUSED_PAD src0_sel:WORD_1
	v_cvt_f32_f16_e32 v2, v4
	v_cvt_f32_f16_sdwa v205, v5 dst_sel:DWORD dst_unused:UNUSED_PAD src0_sel:WORD_1
	v_cvt_f32_f16_e32 v204, v5
	v_cvt_f32_f16_sdwa v5, v6 dst_sel:DWORD dst_unused:UNUSED_PAD src0_sel:WORD_1
	v_cvt_f32_f16_e32 v4, v6
	v_cvt_f32_f16_sdwa v207, v7 dst_sel:DWORD dst_unused:UNUSED_PAD src0_sel:WORD_1
	v_cvt_f32_f16_e32 v206, v7
	s_waitcnt vmcnt(18)
	v_pk_add_f32 v[6:7], v[116:117], v[192:193]
	v_pk_add_f32 v[96:97], v[114:115], v[96:97]
	v_pk_add_f32 v[112:113], v[112:113], v[194:195]
	v_pk_add_f32 v[12:13], v[110:111], v[12:13]
	s_waitcnt vmcnt(16)
	v_pk_add_f32 v[110:111], v[124:125], v[196:197]
	v_pk_add_f32 v[14:15], v[122:123], v[14:15]
	v_pk_add_f32 v[114:115], v[120:121], v[198:199]
	v_pk_add_f32 v[8:9], v[118:119], v[8:9]
	s_waitcnt vmcnt(15)
	v_pk_add_f32 v[116:117], v[128:129], v[200:201]
	v_pk_add_f32 v[10:11], v[126:127], v[10:11]
	s_waitcnt vmcnt(14)
	v_pk_add_f32 v[118:119], v[134:135], v[202:203]
	v_pk_add_f32 v[0:1], v[132:133], v[0:1]
	s_waitcnt vmcnt(13)
	v_pk_add_f32 v[120:121], v[138:139], v[204:205]
	v_pk_add_f32 v[2:3], v[136:137], v[2:3]
	s_waitcnt vmcnt(12)
	v_pk_add_f32 v[122:123], v[142:143], v[206:207]
	v_pk_add_f32 v[4:5], v[140:141], v[4:5]
	s_waitcnt vmcnt(11)
	v_cvt_f32_f16_e32 v124, v144
	v_cvt_f32_f16_sdwa v125, v144 dst_sel:DWORD dst_unused:UNUSED_PAD src0_sel:WORD_1
	v_cvt_f32_f16_e32 v126, v145
	v_cvt_f32_f16_sdwa v127, v145 dst_sel:DWORD dst_unused:UNUSED_PAD src0_sel:WORD_1
	v_cvt_f32_f16_e32 v128, v146
	v_cvt_f32_f16_sdwa v129, v146 dst_sel:DWORD dst_unused:UNUSED_PAD src0_sel:WORD_1
	v_cvt_f32_f16_e32 v132, v147
	v_cvt_f32_f16_sdwa v133, v147 dst_sel:DWORD dst_unused:UNUSED_PAD src0_sel:WORD_1
	s_waitcnt vmcnt(10)
	v_cvt_f32_f16_e32 v134, v148
	v_cvt_f32_f16_sdwa v135, v148 dst_sel:DWORD dst_unused:UNUSED_PAD src0_sel:WORD_1
	v_cvt_f32_f16_e32 v136, v149
	v_cvt_f32_f16_sdwa v137, v149 dst_sel:DWORD dst_unused:UNUSED_PAD src0_sel:WORD_1
	v_cvt_f32_f16_e32 v138, v150
	v_cvt_f32_f16_sdwa v139, v150 dst_sel:DWORD dst_unused:UNUSED_PAD src0_sel:WORD_1
	v_cvt_f32_f16_e32 v140, v151
	v_cvt_f32_f16_sdwa v141, v151 dst_sel:DWORD dst_unused:UNUSED_PAD src0_sel:WORD_1
	s_waitcnt vmcnt(9)
	v_cvt_f32_f16_e32 v142, v152
	v_cvt_f32_f16_sdwa v143, v152 dst_sel:DWORD dst_unused:UNUSED_PAD src0_sel:WORD_1
	v_cvt_f32_f16_e32 v144, v153
	v_cvt_f32_f16_sdwa v145, v153 dst_sel:DWORD dst_unused:UNUSED_PAD src0_sel:WORD_1
	v_cvt_f32_f16_e32 v146, v154
	v_cvt_f32_f16_sdwa v147, v154 dst_sel:DWORD dst_unused:UNUSED_PAD src0_sel:WORD_1
	v_cvt_f32_f16_e32 v148, v155
	v_cvt_f32_f16_sdwa v149, v155 dst_sel:DWORD dst_unused:UNUSED_PAD src0_sel:WORD_1
	s_waitcnt vmcnt(8)
	v_cvt_f32_f16_e32 v150, v156
	v_cvt_f32_f16_sdwa v151, v156 dst_sel:DWORD dst_unused:UNUSED_PAD src0_sel:WORD_1
	v_cvt_f32_f16_e32 v152, v157
	v_cvt_f32_f16_sdwa v153, v157 dst_sel:DWORD dst_unused:UNUSED_PAD src0_sel:WORD_1
	v_cvt_f32_f16_e32 v154, v158
	v_cvt_f32_f16_sdwa v155, v158 dst_sel:DWORD dst_unused:UNUSED_PAD src0_sel:WORD_1
	v_cvt_f32_f16_e32 v156, v159
	v_cvt_f32_f16_sdwa v157, v159 dst_sel:DWORD dst_unused:UNUSED_PAD src0_sel:WORD_1
	v_mul_f32_e32 v158, v97, v97
	v_mul_f32_e32 v159, v7, v7
	v_mul_f32_e32 v192, v13, v13
	v_mul_f32_e32 v193, v113, v113
	v_mul_f32_e32 v194, v15, v15
	v_mul_f32_e32 v195, v111, v111
	v_fmac_f32_e32 v158, v96, v96
	v_fmac_f32_e32 v159, v6, v6
	v_fmac_f32_e32 v192, v12, v12
	v_fmac_f32_e32 v193, v112, v112
	v_mul_f32_e32 v196, v9, v9
	v_mul_f32_e32 v197, v115, v115
	v_fmac_f32_e32 v194, v14, v14
	v_fmac_f32_e32 v195, v110, v110
	v_add_f32_e32 v158, v158, v159
	v_add_f32_e32 v159, v192, v193
	v_mul_f32_e32 v198, v11, v11
	v_mul_f32_e32 v199, v117, v117
	v_fmac_f32_e32 v196, v8, v8
	v_fmac_f32_e32 v197, v114, v114
	v_add_f32_e32 v192, v194, v195
	v_add_f32_e32 v158, v158, v159
	v_mul_f32_e32 v200, v1, v1
	v_mul_f32_e32 v201, v119, v119
	v_fmac_f32_e32 v198, v10, v10
	v_fmac_f32_e32 v199, v116, v116
	v_add_f32_e32 v193, v196, v197
	v_add_f32_e32 v158, v158, v192
	v_mul_f32_e32 v202, v3, v3
	v_mul_f32_e32 v203, v121, v121
	v_fmac_f32_e32 v200, v0, v0
	v_fmac_f32_e32 v201, v118, v118
	v_add_f32_e32 v194, v198, v199
	v_add_f32_e32 v158, v193, v158
	v_mul_f32_e32 v204, v5, v5
	v_mul_f32_e32 v205, v123, v123
	v_fmac_f32_e32 v202, v2, v2
	v_fmac_f32_e32 v203, v120, v120
	v_add_f32_e32 v195, v200, v201
	s_waitcnt vmcnt(7)
	v_pk_add_f32 v[126:127], v[162:163], v[126:127]
	v_pk_add_f32 v[124:125], v[160:161], v[124:125]
	v_add_f32_e32 v158, v158, v194
	v_fmac_f32_e32 v204, v4, v4
	v_fmac_f32_e32 v205, v122, v122
	v_add_f32_e32 v196, v202, v203
	s_waitcnt vmcnt(6)
; template <bool SAMPLE, bool PRE = false> __device__ __forceinline__ void p5_row(Frame& F, int m, float* dst, const f32x4* xpre = nullptr) {
;     ...
;     float s = 0.f;
; #pragma unroll
;     for (int j = 0; j < 16; ++j) s += (v[j].x * v[j].x + v[j].y * v[j].y) + (v[j].z * v[j].z + v[j].w * v[j].w);
;     const float rstd = 1.0f / sqrtf(wave_sum(s) * (1.0f / DM) + EPS);
	v_pk_add_f32 v[132:133], v[166:167], v[132:133]
	v_pk_add_f32 v[128:129], v[164:165], v[128:129]
	v_mul_f32_e32 v159, v125, v125
	v_mul_f32_e32 v160, v127, v127
	v_add_f32_e32 v158, v195, v158
	v_add_f32_e32 v197, v204, v205
	s_waitcnt vmcnt(5)
	v_pk_add_f32 v[136:137], v[170:171], v[136:137]
	v_pk_add_f32 v[134:135], v[168:169], v[134:135]
	v_mul_f32_e32 v161, v129, v129
	v_mul_f32_e32 v162, v133, v133
	v_fmac_f32_e32 v159, v124, v124
	v_fmac_f32_e32 v160, v126, v126
	v_add_f32_e32 v158, v158, v196
	s_waitcnt vmcnt(4)
	v_pk_add_f32 v[140:141], v[174:175], v[140:141]
	v_pk_add_f32 v[138:139], v[172:173], v[138:139]
	v_mul_f32_e32 v163, v135, v135
	v_mul_f32_e32 v164, v137, v137
	v_fmac_f32_e32 v161, v128, v128
	v_fmac_f32_e32 v162, v132, v132
	v_add_f32_e32 v159, v159, v160
	v_add_f32_e32 v158, v197, v158
	s_waitcnt vmcnt(3)
	v_pk_add_f32 v[144:145], v[178:179], v[144:145]
	v_pk_add_f32 v[142:143], v[176:177], v[142:143]
	v_mul_f32_e32 v165, v139, v139
	v_mul_f32_e32 v166, v141, v141
	v_fmac_f32_e32 v163, v134, v134
	v_fmac_f32_e32 v164, v136, v136
	v_add_f32_e32 v160, v161, v162
	v_add_f32_e32 v158, v158, v159
	s_waitcnt vmcnt(2)
	v_pk_add_f32 v[148:149], v[182:183], v[148:149]
	v_pk_add_f32 v[146:147], v[180:181], v[146:147]
	v_mul_f32_e32 v167, v143, v143
	v_mul_f32_e32 v168, v145, v145
	v_fmac_f32_e32 v165, v138, v138
	v_fmac_f32_e32 v166, v140, v140
	v_add_f32_e32 v161, v163, v164
	v_add_f32_e32 v158, v160, v158
	s_waitcnt vmcnt(1)
	v_pk_add_f32 v[152:153], v[186:187], v[152:153]
	v_pk_add_f32 v[150:151], v[184:185], v[150:151]
	v_mul_f32_e32 v169, v147, v147
	v_mul_f32_e32 v170, v149, v149
	v_fmac_f32_e32 v167, v142, v142
	v_fmac_f32_e32 v168, v144, v144
	v_add_f32_e32 v162, v165, v166
	v_add_f32_e32 v158, v158, v161
	s_waitcnt vmcnt(0)
	v_pk_add_f32 v[156:157], v[190:191], v[156:157]
	v_pk_add_f32 v[154:155], v[188:189], v[154:155]
	v_mul_f32_e32 v171, v151, v151
	v_mul_f32_e32 v172, v153, v153
	v_fmac_f32_e32 v169, v146, v146
	v_fmac_f32_e32 v170, v148, v148
	v_add_f32_e32 v163, v167, v168
	v_add_f32_e32 v158, v162, v158
	v_mul_f32_e32 v173, v155, v155
	v_mul_f32_e32 v174, v157, v157
	v_fmac_f32_e32 v171, v150, v150
	v_fmac_f32_e32 v172, v152, v152
	v_add_f32_e32 v164, v169, v170
	v_add_f32_e32 v158, v158, v163
	v_fmac_f32_e32 v173, v154, v154
	v_fmac_f32_e32 v174, v156, v156
	v_add_f32_e32 v165, v171, v172
	v_add_f32_e32 v158, v164, v158
	v_add_f32_e32 v166, v173, v174
	v_add_f32_e32 v158, v158, v165
	v_add_f32_e32 v158, v166, v158
	s_nop 1
	v_add_f32_dpp v158, v158, v158 quad_perm:[1,0,3,2] row_mask:0xf bank_mask:0xf bound_ctrl:1
	s_nop 1
	v_add_f32_dpp v158, v158, v158 quad_perm:[2,3,0,1] row_mask:0xf bank_mask:0xf bound_ctrl:1
	s_nop 1
	v_add_f32_dpp v158, v158, v158 row_half_mirror row_mask:0xf bank_mask:0xf bound_ctrl:1
	s_nop 1
	v_add_f32_dpp v158, v158, v158 row_mirror row_mask:0xf bank_mask:0xf bound_ctrl:1
	s_nop 1
	v_mov_b32_dpp v109, v158 row_bcast:15 row_mask:0xa bank_mask:0xf
	v_add_f32_e32 v109, v158, v109
	s_nop 1
	v_mov_b32_dpp v208, v109 row_bcast:31 row_mask:0xc bank_mask:0xf
	v_add_f32_e32 v109, v109, v208
	s_nop 0
	v_readlane_b32 s0, v109, 63
	s_nop 1
	v_fma_f32 v109, s0, v107, v106
	v_mul_f32_e32 v158, 0x4f800000, v109
	v_cmp_gt_f32_e32 vcc, s26, v109
	s_nop 1
	v_cndmask_b32_e32 v109, v109, v158, vcc
	v_sqrt_f32_e32 v158, v109
	s_nop 0
	v_add_u32_e32 v159, -1, v158
	v_add_u32_e32 v160, 1, v158
	v_fma_f32 v161, -v159, v158, v109
	v_fma_f32 v162, -v160, v158, v109
	v_cmp_ge_f32_e64 s[0:1], 0, v161
	s_nop 1
	v_cndmask_b32_e64 v158, v158, v159, s[0:1]
	v_cmp_lt_f32_e64 s[0:1], 0, v162
	s_nop 1
	v_cndmask_b32_e64 v158, v158, v160, s[0:1]
	v_mul_f32_e32 v159, 0x37800000, v158
	v_cndmask_b32_e32 v158, v158, v159, vcc
	v_cmp_class_f32_e32 vcc, v109, v108
	s_nop 1
	v_cndmask_b32_e32 v109, v158, v109, vcc
	v_div_scale_f32 v158, s[0:1], v109, v109, 1.0
	v_rcp_f32_e32 v160, v158
	v_div_scale_f32 v159, vcc, 1.0, v109, 1.0
	v_fma_f32 v161, -v158, v160, 1.0
	v_fmac_f32_e32 v160, v161, v160
	v_mul_f32_e32 v161, v159, v160
	v_fma_f32 v162, -v158, v161, v159
	v_fmac_f32_e32 v161, v162, v160
	v_fma_f32 v158, -v158, v161, v159
	v_div_fmas_f32 v158, v158, v160, v161
	v_div_fixup_f32 v158, v158, v109, 1.0
	v_pk_mul_f32 v[96:97], v[96:97], v[158:159] op_sel_hi:[1,0]
	v_pk_mul_f32 v[6:7], v[6:7], v[158:159] op_sel_hi:[1,0]
	v_pk_mul_f32 v[12:13], v[12:13], v[158:159] op_sel_hi:[1,0]
	v_pk_mul_f32 v[112:113], v[112:113], v[158:159] op_sel_hi:[1,0]
	v_pk_mul_f32 v[14:15], v[14:15], v[158:159] op_sel_hi:[1,0]
; template <bool SAMPLE, bool PRE = false> __device__ __forceinline__ void p5_row(Frame& F, int m, float* dst, const f32x4* xpre = nullptr) {
;     ...
;     for (int j = 0; j < 8; ++j) { gv[2 * j] = g8[128 * j]; gv[2 * j + 1] = g8[128 * j + 1]; }
; #pragma unroll
;     for (int j = 0; j < 8; ++j) { y8[128 * j] = v[2 * j] * rstd * gv[2 * j]; y8[128 * j + 1] = v[2 * j + 1] * rstd * gv[2 * j + 1]; }
; }
; __device__ __forceinline__ void p5_final_norm(Frame& F, float* dst, const f32x4 (&xpre)[16]) {
;     const int gw = F.vcu * NWAVES + F.wave, NGW = F.G * NWAVES;
;     for (int r = F.wave * F.G + F.vcu; r < MS; r += NGW) p5_row<true>(F, MP + r, dst);
;     if (gw < MP) p5_row<false, true>(F, gw, dst, xpre);
;     for (int m = gw + NGW; m < MP; m += NGW) p5_row<false>(F, m, dst);
	v_pk_mul_f32 v[110:111], v[110:111], v[158:159] op_sel_hi:[1,0]
	v_pk_mul_f32 v[160:161], v[8:9], v[158:159] op_sel_hi:[1,0]
	v_pk_mul_f32 v[114:115], v[114:115], v[158:159] op_sel_hi:[1,0]
	v_pk_mul_f32 v[162:163], v[10:11], v[158:159] op_sel_hi:[1,0]
	v_pk_mul_f32 v[116:117], v[116:117], v[158:159] op_sel_hi:[1,0]
	v_pk_mul_f32 v[164:165], v[0:1], v[158:159] op_sel_hi:[1,0]
	v_pk_mul_f32 v[118:119], v[118:119], v[158:159] op_sel_hi:[1,0]
	v_pk_mul_f32 v[166:167], v[2:3], v[158:159] op_sel_hi:[1,0]
	v_pk_mul_f32 v[120:121], v[120:121], v[158:159] op_sel_hi:[1,0]
	v_pk_mul_f32 v[168:169], v[4:5], v[158:159] op_sel_hi:[1,0]
	v_pk_mul_f32 v[122:123], v[122:123], v[158:159] op_sel_hi:[1,0]
	v_pk_mul_f32 v[124:125], v[124:125], v[158:159] op_sel_hi:[1,0]
	v_pk_mul_f32 v[126:127], v[126:127], v[158:159] op_sel_hi:[1,0]
	v_pk_mul_f32 v[128:129], v[128:129], v[158:159] op_sel_hi:[1,0]
	v_pk_mul_f32 v[132:133], v[132:133], v[158:159] op_sel_hi:[1,0]
	v_pk_mul_f32 v[134:135], v[134:135], v[158:159] op_sel_hi:[1,0]
	v_pk_mul_f32 v[136:137], v[136:137], v[158:159] op_sel_hi:[1,0]
	v_pk_mul_f32 v[138:139], v[138:139], v[158:159] op_sel_hi:[1,0]
	v_pk_mul_f32 v[140:141], v[140:141], v[158:159] op_sel_hi:[1,0]
	v_pk_mul_f32 v[142:143], v[142:143], v[158:159] op_sel_hi:[1,0]
	v_pk_mul_f32 v[144:145], v[144:145], v[158:159] op_sel_hi:[1,0]
	v_pk_mul_f32 v[146:147], v[146:147], v[158:159] op_sel_hi:[1,0]
	v_pk_mul_f32 v[148:149], v[148:149], v[158:159] op_sel_hi:[1,0]
	v_pk_mul_f32 v[150:151], v[150:151], v[158:159] op_sel_hi:[1,0]
	v_pk_mul_f32 v[152:153], v[152:153], v[158:159] op_sel_hi:[1,0]
	v_pk_mul_f32 v[154:155], v[154:155], v[158:159] op_sel_hi:[1,0]
	v_pk_mul_f32 v[156:157], v[156:157], v[158:159] op_sel_hi:[1,0]
	v_pk_mul_f32 v[2:3], v[78:79], v[6:7]
	v_pk_mul_f32 v[0:1], v[76:77], v[96:97]
	v_pk_mul_f32 v[6:7], v[70:71], v[112:113]
	v_pk_mul_f32 v[4:5], v[68:69], v[12:13]
	v_pk_mul_f32 v[10:11], v[74:75], v[110:111]
	v_pk_mul_f32 v[8:9], v[72:73], v[14:15]
	v_pk_mul_f32 v[14:15], v[62:63], v[114:115]
	v_pk_mul_f32 v[12:13], v[60:61], v[160:161]
	v_pk_mul_f32 v[62:63], v[66:67], v[116:117]
	v_pk_mul_f32 v[60:61], v[64:65], v[162:163]
	v_pk_mul_f32 v[54:55], v[54:55], v[118:119]
	v_pk_mul_f32 v[52:53], v[52:53], v[164:165]
	v_pk_mul_f32 v[58:59], v[120:121], v[58:59]
	v_pk_mul_f32 v[56:57], v[166:167], v[56:57]
	v_pk_mul_f32 v[46:47], v[122:123], v[46:47]
	v_pk_mul_f32 v[44:45], v[168:169], v[44:45]
	v_pk_mul_f32 v[50:51], v[126:127], v[50:51]
	v_pk_mul_f32 v[48:49], v[124:125], v[48:49]
	v_pk_mul_f32 v[38:39], v[132:133], v[38:39]
	v_pk_mul_f32 v[36:37], v[128:129], v[36:37]
	v_pk_mul_f32 v[42:43], v[136:137], v[42:43]
	v_pk_mul_f32 v[40:41], v[134:135], v[40:41]
	v_pk_mul_f32 v[30:31], v[140:141], v[30:31]
	v_pk_mul_f32 v[28:29], v[138:139], v[28:29]
	v_pk_mul_f32 v[34:35], v[144:145], v[34:35]
	v_pk_mul_f32 v[32:33], v[142:143], v[32:33]
	v_pk_mul_f32 v[22:23], v[148:149], v[22:23]
	v_pk_mul_f32 v[20:21], v[146:147], v[20:21]
	v_pk_mul_f32 v[26:27], v[152:153], v[26:27]
	v_pk_mul_f32 v[24:25], v[150:151], v[24:25]
	v_pk_mul_f32 v[18:19], v[156:157], v[18:19]
	v_pk_mul_f32 v[16:17], v[154:155], v[16:17]
	global_store_dwordx4 v[98:99], v[0:3], off
	global_store_dwordx4 v[98:99], v[4:7], off offset:16
	global_store_dwordx4 v[98:99], v[8:11], off offset:2048
	global_store_dwordx4 v[98:99], v[12:15], off offset:2064
	global_store_dwordx4 v[102:103], v[60:63], off offset:-4096
	global_store_dwordx4 v[104:105], v[52:55], off offset:16
	global_store_dwordx4 v[104:105], v[56:59], off offset:2048
	global_store_dwordx4 v[104:105], v[44:47], off offset:2064
	global_store_dwordx4 v[102:103], v[48:51], off
	global_store_dwordx4 v[102:103], v[36:39], off offset:16
	global_store_dwordx4 v[102:103], v[40:43], off offset:2048
	global_store_dwordx4 v[102:103], v[28:31], off offset:2064
	global_store_dwordx4 v[100:101], v[32:35], off
	global_store_dwordx4 v[100:101], v[20:23], off offset:16
	global_store_dwordx4 v[100:101], v[24:27], off offset:2048
	global_store_dwordx4 v[100:101], v[16:19], off offset:2064
	s_cbranch_scc1 .LBB0_842
.LBB0_843:
	s_cmp_eq_u32 s100, 1
	s_cbranch_scc1 .Lp5_end
	s_sub_u32 s101, s33, 2
	s_cmp_lt_u32 s101, 2
	s_cbranch_scc0 .Lp5_end
	s_mov_b32 s100, 1
	s_sub_u32 s6, s6, 0x2008000
	s_subb_u32 s7, s7, 0
	s_sub_u32 s8, s8, 0x2008000
	s_subb_u32 s9, s9, 0
	v_subrev_co_u32_e32 v94, vcc, 0x1004000, v94
	s_nop 1
	v_subbrev_co_u32_e32 v95, vcc, 0, v95, vcc
	s_mov_b32 s22, 0x7fff0000
	s_movk_i32 s99, 0x2000
	s_branch .LBB0_842
